# v014 + loop-edge edit: K-loop index updates and loop test hoisted above the last MFMA block (out of the post-barrier head) in the P1/P4/P5/P6 GEMM loops
# speedup vs baseline: 1.0009x; 1.0009x over previous
.LBB0_151:
	ds_read_b128 v[130:133], v223
	ds_read_b128 v[134:137], v223 offset:1024
	ds_read_b128 v[156:159], v223 offset:2048
	ds_read_b128 v[160:163], v223 offset:3072
	ds_read_b128 v[164:167], v224
	ds_read_b128 v[168:171], v224 offset:1024
	ds_read_b128 v[172:175], v224 offset:2048
	ds_read_b128 v[186:189], v224 offset:3072
	s_add_u32 s6, s0, 0xfffc0080
	s_addc_u32 s7, s1, -1
	s_cmp_eq_u32 s58, 12
	s_cselect_b32 s9, s3, s7
	s_cselect_b32 s8, s33, s6
	s_cselect_b32 s7, s45, s57
	s_cselect_b32 s6, s47, s56
	v_lshl_add_u64 v[178:179], s[0:1], 0, v[150:151]
	s_add_i32 m0, s55, 0xc000
	ds_read_b128 v[190:193], v225
	ds_read_b128 v[194:197], v225 offset:1024
	ds_read_b128 v[198:201], v225 offset:2048
	ds_read_b128 v[202:205], v225 offset:3072
	ds_read_b128 v[206:209], v225 offset:4096
	ds_read_b128 v[210:213], v225 offset:5120
	ds_read_b128 v[214:217], v225 offset:6144
	ds_read_b128 v[218:221], v225 offset:7168
	global_load_lds_dwordx4 v[178:179], off
	v_lshl_add_u64 v[178:179], s[0:1], 0, v[152:153]
	s_add_i32 m0, s55, 0xe000
	s_nop 0
	global_load_lds_dwordx4 v[178:179], off
	s_waitcnt vmcnt(8)
	s_waitcnt lgkmcnt(0)
	s_barrier
	s_setprio 1
	s_waitcnt lgkmcnt(0)
	v_mfma_f32_16x16x32_bf16 v[126:129], v[130:133], v[190:193], v[126:129]
	v_mfma_f32_16x16x32_bf16 v[122:125], v[156:159], v[190:193], v[122:125]
	v_mfma_f32_16x16x32_bf16 v[110:113], v[130:133], v[198:201], v[110:113]
	v_mfma_f32_16x16x32_bf16 v[106:109], v[156:159], v[198:201], v[106:109]
	v_mfma_f32_16x16x32_bf16 v[94:97], v[130:133], v[206:209], v[94:97]
	v_mfma_f32_16x16x32_bf16 v[90:93], v[156:159], v[206:209], v[90:93]
	v_mfma_f32_16x16x32_bf16 v[78:81], v[130:133], v[214:217], v[78:81]
	v_mfma_f32_16x16x32_bf16 v[74:77], v[156:159], v[214:217], v[74:77]
	v_mfma_f32_16x16x32_bf16 v[126:129], v[134:137], v[194:197], v[126:129]
	v_mfma_f32_16x16x32_bf16 v[122:125], v[160:163], v[194:197], v[122:125]
	v_mfma_f32_16x16x32_bf16 v[110:113], v[134:137], v[202:205], v[110:113]
	v_mfma_f32_16x16x32_bf16 v[106:109], v[160:163], v[202:205], v[106:109]
	v_mfma_f32_16x16x32_bf16 v[94:97], v[134:137], v[210:213], v[94:97]
	v_mfma_f32_16x16x32_bf16 v[90:93], v[160:163], v[210:213], v[90:93]
	v_mfma_f32_16x16x32_bf16 v[78:81], v[134:137], v[218:221], v[78:81]
	v_mfma_f32_16x16x32_bf16 v[74:77], v[160:163], v[218:221], v[74:77]
	s_setprio 0
	s_setprio 1
	v_mfma_f32_16x16x32_bf16 v[118:121], v[164:167], v[190:193], v[118:121]
	v_mfma_f32_16x16x32_bf16 v[114:117], v[172:175], v[190:193], v[114:117]
	v_mfma_f32_16x16x32_bf16 v[102:105], v[164:167], v[198:201], v[102:105]
	v_mfma_f32_16x16x32_bf16 v[98:101], v[172:175], v[198:201], v[98:101]
	v_mfma_f32_16x16x32_bf16 v[86:89], v[164:167], v[206:209], v[86:89]
	v_mfma_f32_16x16x32_bf16 v[82:85], v[172:175], v[206:209], v[82:85]
	v_mfma_f32_16x16x32_bf16 v[70:73], v[164:167], v[214:217], v[70:73]
	v_mfma_f32_16x16x32_bf16 v[66:69], v[172:175], v[214:217], v[66:69]
	v_mfma_f32_16x16x32_bf16 v[118:121], v[168:171], v[194:197], v[118:121]
	v_mfma_f32_16x16x32_bf16 v[114:117], v[186:189], v[194:197], v[114:117]
	v_mfma_f32_16x16x32_bf16 v[102:105], v[168:171], v[202:205], v[102:105]
	v_mfma_f32_16x16x32_bf16 v[98:101], v[186:189], v[202:205], v[98:101]
	v_mfma_f32_16x16x32_bf16 v[86:89], v[168:171], v[210:213], v[86:89]
	v_mfma_f32_16x16x32_bf16 v[82:85], v[186:189], v[210:213], v[82:85]
	v_mfma_f32_16x16x32_bf16 v[70:73], v[168:171], v[218:221], v[70:73]
	v_mfma_f32_16x16x32_bf16 v[66:69], v[186:189], v[218:221], v[66:69]
	s_setprio 0
	s_barrier
	s_add_i32 s59, s86, s71
	v_lshl_add_u64 v[178:179], s[6:7], 0, v[140:141]
	s_mov_b32 m0, s59
	ds_read_b128 v[190:193], v225 offset:16384
	ds_read_b128 v[194:197], v225 offset:17408
	ds_read_b128 v[198:201], v225 offset:18432
	ds_read_b128 v[202:205], v225 offset:19456
	ds_read_b128 v[206:209], v225 offset:20480
	ds_read_b128 v[210:213], v225 offset:21504
	ds_read_b128 v[214:217], v225 offset:22528
	ds_read_b128 v[218:221], v225 offset:23552
	global_load_lds_dwordx4 v[178:179], off
	s_add_i32 m0, s59, 0x2000
	s_add_u32 s60, s6, 0x40000
	v_lshl_add_u64 v[182:183], s[6:7], 0, v[144:145]
	s_addc_u32 s61, s7, 0
	s_add_i32 s59, s87, s71
	global_load_lds_dwordx4 v[182:183], off
	v_lshl_add_u64 v[232:233], s[60:61], 0, v[140:141]
	s_mov_b32 m0, s59
	v_lshl_add_u64 v[234:235], s[8:9], 0, v[142:143]
	global_load_lds_dwordx4 v[232:233], off
	v_lshl_add_u64 v[232:233], s[60:61], 0, v[144:145]
	s_add_i32 m0, s59, 0x2000
	s_nop 0
	global_load_lds_dwordx4 v[232:233], off
	v_lshl_add_u64 v[232:233], s[8:9], 0, v[138:139]
	s_mov_b32 m0, s55
	s_nop 0
	global_load_lds_dwordx4 v[232:233], off
	s_mov_b32 m0, s72
	s_nop 0
	global_load_lds_dwordx4 v[234:235], off
	s_waitcnt vmcnt(8)
	s_waitcnt lgkmcnt(0)
	s_barrier
	s_setprio 1
	s_waitcnt lgkmcnt(0)
	v_mfma_f32_16x16x32_bf16 v[62:65], v[130:133], v[190:193], v[62:65]
	v_mfma_f32_16x16x32_bf16 v[58:61], v[156:159], v[190:193], v[58:61]
	v_mfma_f32_16x16x32_bf16 v[46:49], v[130:133], v[198:201], v[46:49]
	v_mfma_f32_16x16x32_bf16 v[42:45], v[156:159], v[198:201], v[42:45]
	v_mfma_f32_16x16x32_bf16 v[30:33], v[130:133], v[206:209], v[30:33]
	v_mfma_f32_16x16x32_bf16 v[26:29], v[156:159], v[206:209], v[26:29]
	v_mfma_f32_16x16x32_bf16 v[14:17], v[130:133], v[214:217], v[14:17]
	v_mfma_f32_16x16x32_bf16 v[10:13], v[156:159], v[214:217], v[10:13]
	v_mfma_f32_16x16x32_bf16 v[62:65], v[134:137], v[194:197], v[62:65]
	v_mfma_f32_16x16x32_bf16 v[58:61], v[160:163], v[194:197], v[58:61]
	v_mfma_f32_16x16x32_bf16 v[46:49], v[134:137], v[202:205], v[46:49]
	v_mfma_f32_16x16x32_bf16 v[42:45], v[160:163], v[202:205], v[42:45]
	v_mfma_f32_16x16x32_bf16 v[30:33], v[134:137], v[210:213], v[30:33]
	v_mfma_f32_16x16x32_bf16 v[26:29], v[160:163], v[210:213], v[26:29]
	v_mfma_f32_16x16x32_bf16 v[14:17], v[134:137], v[218:221], v[14:17]
	v_mfma_f32_16x16x32_bf16 v[10:13], v[160:163], v[218:221], v[10:13]
	s_setprio 0
	s_setprio 1
	v_mfma_f32_16x16x32_bf16 v[54:57], v[164:167], v[190:193], v[54:57]
	v_mfma_f32_16x16x32_bf16 v[50:53], v[172:175], v[190:193], v[50:53]
	v_mfma_f32_16x16x32_bf16 v[38:41], v[164:167], v[198:201], v[38:41]
	v_mfma_f32_16x16x32_bf16 v[34:37], v[172:175], v[198:201], v[34:37]
	v_mfma_f32_16x16x32_bf16 v[22:25], v[164:167], v[206:209], v[22:25]
	v_mfma_f32_16x16x32_bf16 v[18:21], v[172:175], v[206:209], v[18:21]
	v_mfma_f32_16x16x32_bf16 v[6:9], v[164:167], v[214:217], v[6:9]
	v_mfma_f32_16x16x32_bf16 v[2:5], v[172:175], v[214:217], v[2:5]
	v_mfma_f32_16x16x32_bf16 v[54:57], v[168:171], v[194:197], v[54:57]
	v_mfma_f32_16x16x32_bf16 v[50:53], v[186:189], v[194:197], v[50:53]
	v_mfma_f32_16x16x32_bf16 v[38:41], v[168:171], v[202:205], v[38:41]
	v_mfma_f32_16x16x32_bf16 v[34:37], v[186:189], v[202:205], v[34:37]
	v_mfma_f32_16x16x32_bf16 v[22:25], v[168:171], v[210:213], v[22:25]
	v_mfma_f32_16x16x32_bf16 v[18:21], v[186:189], v[210:213], v[18:21]
	v_mfma_f32_16x16x32_bf16 v[6:9], v[168:171], v[218:221], v[6:9]
	v_mfma_f32_16x16x32_bf16 v[2:5], v[186:189], v[218:221], v[2:5]
	s_setprio 0
	s_barrier
	s_add_i32 s59, 0, 0x18000
	s_add_i32 s60, 0, 0x1c000
	v_add_u32_e32 v160, s59, v181
	v_add_u32_e32 v176, s60, v181
	ds_read_b128 v[130:133], v160
	ds_read_b128 v[134:137], v160 offset:1024
	ds_read_b128 v[156:159], v160 offset:2048
	ds_read_b128 v[160:163], v160 offset:3072
	ds_read_b128 v[164:167], v176
	ds_read_b128 v[168:171], v176 offset:1024
	ds_read_b128 v[172:175], v176 offset:2048
	ds_read_b128 v[186:189], v176 offset:3072
	s_add_u32 s8, s8, 0x40000
	s_addc_u32 s9, s9, 0
	s_mov_b32 m0, s73
	v_lshl_add_u64 v[236:237], s[8:9], 0, v[138:139]
	ds_read_b128 v[190:193], v225 offset:32768
	ds_read_b128 v[194:197], v225 offset:33792
	ds_read_b128 v[198:201], v225 offset:34816
	ds_read_b128 v[202:205], v225 offset:35840
	ds_read_b128 v[206:209], v225 offset:36864
	ds_read_b128 v[210:213], v225 offset:37888
	ds_read_b128 v[214:217], v225 offset:38912
	ds_read_b128 v[218:221], v225 offset:39936
	global_load_lds_dwordx4 v[236:237], off
	v_lshl_add_u64 v[236:237], s[8:9], 0, v[142:143]
	s_mov_b32 m0, s74
	s_nop 0
	global_load_lds_dwordx4 v[236:237], off
	s_waitcnt vmcnt(8)
	s_waitcnt lgkmcnt(0)
	s_barrier
	s_setprio 1
	s_waitcnt lgkmcnt(0)
	v_mfma_f32_16x16x32_bf16 v[126:129], v[130:133], v[190:193], v[126:129]
	v_mfma_f32_16x16x32_bf16 v[122:125], v[156:159], v[190:193], v[122:125]
	v_mfma_f32_16x16x32_bf16 v[110:113], v[130:133], v[198:201], v[110:113]
	v_mfma_f32_16x16x32_bf16 v[106:109], v[156:159], v[198:201], v[106:109]
	v_mfma_f32_16x16x32_bf16 v[94:97], v[130:133], v[206:209], v[94:97]
	v_mfma_f32_16x16x32_bf16 v[90:93], v[156:159], v[206:209], v[90:93]
	v_mfma_f32_16x16x32_bf16 v[78:81], v[130:133], v[214:217], v[78:81]
	v_mfma_f32_16x16x32_bf16 v[74:77], v[156:159], v[214:217], v[74:77]
	v_mfma_f32_16x16x32_bf16 v[126:129], v[134:137], v[194:197], v[126:129]
	v_mfma_f32_16x16x32_bf16 v[122:125], v[160:163], v[194:197], v[122:125]
	v_mfma_f32_16x16x32_bf16 v[110:113], v[134:137], v[202:205], v[110:113]
	v_mfma_f32_16x16x32_bf16 v[106:109], v[160:163], v[202:205], v[106:109]
	v_mfma_f32_16x16x32_bf16 v[94:97], v[134:137], v[210:213], v[94:97]
	v_mfma_f32_16x16x32_bf16 v[90:93], v[160:163], v[210:213], v[90:93]
	v_mfma_f32_16x16x32_bf16 v[78:81], v[134:137], v[218:221], v[78:81]
	v_mfma_f32_16x16x32_bf16 v[74:77], v[160:163], v[218:221], v[74:77]
	s_setprio 0
	s_setprio 1
	v_mfma_f32_16x16x32_bf16 v[118:121], v[164:167], v[190:193], v[118:121]
	v_mfma_f32_16x16x32_bf16 v[114:117], v[172:175], v[190:193], v[114:117]
	v_mfma_f32_16x16x32_bf16 v[102:105], v[164:167], v[198:201], v[102:105]
	v_mfma_f32_16x16x32_bf16 v[98:101], v[172:175], v[198:201], v[98:101]
	v_mfma_f32_16x16x32_bf16 v[86:89], v[164:167], v[206:209], v[86:89]
	v_mfma_f32_16x16x32_bf16 v[82:85], v[172:175], v[206:209], v[82:85]
	v_mfma_f32_16x16x32_bf16 v[70:73], v[164:167], v[214:217], v[70:73]
	v_mfma_f32_16x16x32_bf16 v[66:69], v[172:175], v[214:217], v[66:69]
	v_mfma_f32_16x16x32_bf16 v[118:121], v[168:171], v[194:197], v[118:121]
	v_mfma_f32_16x16x32_bf16 v[114:117], v[186:189], v[194:197], v[114:117]
	v_mfma_f32_16x16x32_bf16 v[102:105], v[168:171], v[202:205], v[102:105]
	v_mfma_f32_16x16x32_bf16 v[98:101], v[186:189], v[202:205], v[98:101]
	v_mfma_f32_16x16x32_bf16 v[86:89], v[168:171], v[210:213], v[86:89]
	v_mfma_f32_16x16x32_bf16 v[82:85], v[186:189], v[210:213], v[82:85]
	v_mfma_f32_16x16x32_bf16 v[70:73], v[168:171], v[218:221], v[70:73]
	v_mfma_f32_16x16x32_bf16 v[66:69], v[186:189], v[218:221], v[66:69]
	s_setprio 0
	s_barrier
	s_add_i32 s8, s59, s71
	v_lshl_add_u64 v[178:179], v[178:179], 0, s[38:39]
	s_mov_b32 m0, s8
	ds_read_b128 v[190:193], v225 offset:49152
	ds_read_b128 v[194:197], v225 offset:50176
	ds_read_b128 v[198:201], v225 offset:51200
	ds_read_b128 v[202:205], v225 offset:52224
	ds_read_b128 v[206:209], v225 offset:53248
	ds_read_b128 v[210:213], v225 offset:54272
	ds_read_b128 v[214:217], v225 offset:55296
	ds_read_b128 v[218:221], v225 offset:56320
	global_load_lds_dwordx4 v[178:179], off
	s_add_i32 m0, s8, 0x2000
	s_add_u32 s6, s6, 0x40080
	v_lshl_add_u64 v[178:179], v[182:183], 0, s[38:39]
	s_addc_u32 s7, s7, 0
	s_add_i32 s8, s60, s71
	global_load_lds_dwordx4 v[178:179], off
	v_lshl_add_u64 v[178:179], s[6:7], 0, v[140:141]
	s_mov_b32 m0, s8
	s_nop 0
	global_load_lds_dwordx4 v[178:179], off
	v_lshl_add_u64 v[178:179], s[6:7], 0, v[144:145]
	s_add_i32 m0, s8, 0x2000
	s_nop 0
	global_load_lds_dwordx4 v[178:179], off
	v_lshl_add_u64 v[178:179], v[232:233], 0, s[38:39]
	s_mov_b32 m0, s79
	s_nop 0
	global_load_lds_dwordx4 v[178:179], off
	v_lshl_add_u64 v[178:179], v[234:235], 0, s[38:39]
	s_mov_b32 m0, s80
	s_nop 0
	global_load_lds_dwordx4 v[178:179], off
	s_waitcnt vmcnt(8)
	s_waitcnt lgkmcnt(0)
	s_barrier
	s_setprio 1
	s_waitcnt lgkmcnt(0)
	v_mfma_f32_16x16x32_bf16 v[62:65], v[130:133], v[190:193], v[62:65]
	v_mfma_f32_16x16x32_bf16 v[58:61], v[156:159], v[190:193], v[58:61]
	v_mfma_f32_16x16x32_bf16 v[46:49], v[130:133], v[198:201], v[46:49]
	v_mfma_f32_16x16x32_bf16 v[42:45], v[156:159], v[198:201], v[42:45]
	v_mfma_f32_16x16x32_bf16 v[30:33], v[130:133], v[206:209], v[30:33]
	v_mfma_f32_16x16x32_bf16 v[26:29], v[156:159], v[206:209], v[26:29]
	v_mfma_f32_16x16x32_bf16 v[14:17], v[130:133], v[214:217], v[14:17]
	v_mfma_f32_16x16x32_bf16 v[10:13], v[156:159], v[214:217], v[10:13]
	v_mfma_f32_16x16x32_bf16 v[62:65], v[134:137], v[194:197], v[62:65]
	v_mfma_f32_16x16x32_bf16 v[58:61], v[160:163], v[194:197], v[58:61]
	v_mfma_f32_16x16x32_bf16 v[46:49], v[134:137], v[202:205], v[46:49]
	v_mfma_f32_16x16x32_bf16 v[42:45], v[160:163], v[202:205], v[42:45]
	v_mfma_f32_16x16x32_bf16 v[30:33], v[134:137], v[210:213], v[30:33]
	v_mfma_f32_16x16x32_bf16 v[26:29], v[160:163], v[210:213], v[26:29]
	v_mfma_f32_16x16x32_bf16 v[14:17], v[134:137], v[218:221], v[14:17]
	v_mfma_f32_16x16x32_bf16 v[10:13], v[160:163], v[218:221], v[10:13]
	s_setprio 0
	s_setprio 1
	s_add_i32 s58, s58, 2
	s_add_u32 s0, s0, 0x100
	s_addc_u32 s1, s1, 0
	s_add_u32 s56, s56, 0x100
	s_addc_u32 s57, s57, 0
	s_cmp_gt_u32 s58, 13
	v_mfma_f32_16x16x32_bf16 v[54:57], v[164:167], v[190:193], v[54:57]
	v_mfma_f32_16x16x32_bf16 v[50:53], v[172:175], v[190:193], v[50:53]
	v_mfma_f32_16x16x32_bf16 v[38:41], v[164:167], v[198:201], v[38:41]
	v_mfma_f32_16x16x32_bf16 v[34:37], v[172:175], v[198:201], v[34:37]
	v_mfma_f32_16x16x32_bf16 v[22:25], v[164:167], v[206:209], v[22:25]
	v_mfma_f32_16x16x32_bf16 v[18:21], v[172:175], v[206:209], v[18:21]
	v_mfma_f32_16x16x32_bf16 v[6:9], v[164:167], v[214:217], v[6:9]
	v_mfma_f32_16x16x32_bf16 v[2:5], v[172:175], v[214:217], v[2:5]
	v_mfma_f32_16x16x32_bf16 v[54:57], v[168:171], v[194:197], v[54:57]
	v_mfma_f32_16x16x32_bf16 v[50:53], v[186:189], v[194:197], v[50:53]
	v_mfma_f32_16x16x32_bf16 v[38:41], v[168:171], v[202:205], v[38:41]
	v_mfma_f32_16x16x32_bf16 v[34:37], v[186:189], v[202:205], v[34:37]
	v_mfma_f32_16x16x32_bf16 v[22:25], v[168:171], v[210:213], v[22:25]
	v_mfma_f32_16x16x32_bf16 v[18:21], v[186:189], v[210:213], v[18:21]
	v_mfma_f32_16x16x32_bf16 v[6:9], v[168:171], v[218:221], v[6:9]
	v_mfma_f32_16x16x32_bf16 v[2:5], v[186:189], v[218:221], v[2:5]
	s_setprio 0
	s_barrier
	s_cbranch_scc0 .LBB0_151
	s_and_b64 vcc, exec, s[40:41]
	s_cbranch_vccz .LBB0_154
	s_barrier

.LBB0_845:
	ds_read_b128 v[130:133], v208
	ds_read_b128 v[134:137], v208 offset:1024
	ds_read_b128 v[138:141], v208 offset:2048
	ds_read_b128 v[142:145], v208 offset:3072
	ds_read_b128 v[146:149], v209
	ds_read_b128 v[150:153], v209 offset:1024
	ds_read_b128 v[154:157], v209 offset:2048
	ds_read_b128 v[158:161], v209 offset:3072
	s_add_u32 s30, s28, 0xfffc0080
	s_addc_u32 s31, s29, -1
	s_cmp_eq_u32 s54, 12
	s_cselect_b32 s35, s19, s31
	s_cselect_b32 s34, s25, s30
	s_cselect_b32 s31, s17, s53
	s_cselect_b32 s30, s51, s52
	v_lshl_add_u64 v[216:217], s[28:29], 0, v[186:187]
	s_add_i32 m0, s27, 0xc000
	ds_read_b128 v[162:165], v210
	ds_read_b128 v[166:169], v210 offset:1024
	ds_read_b128 v[170:173], v210 offset:2048
	ds_read_b128 v[174:177], v210 offset:3072
	ds_read_b128 v[194:197], v210 offset:4096
	ds_read_b128 v[198:201], v210 offset:5120
	ds_read_b128 v[202:205], v210 offset:6144
	ds_read_b128 v[212:215], v210 offset:7168
	global_load_lds_dwordx4 v[216:217], off
	v_lshl_add_u64 v[216:217], s[28:29], 0, v[188:189]
	s_add_i32 m0, s27, 0xe000
	s_nop 0
	global_load_lds_dwordx4 v[216:217], off
	s_waitcnt vmcnt(8)
	s_waitcnt lgkmcnt(0)
	s_barrier
	s_setprio 1
	s_waitcnt lgkmcnt(0)
	v_mfma_f32_16x16x32_bf16 v[126:129], v[130:133], v[162:165], v[126:129]
	v_mfma_f32_16x16x32_bf16 v[122:125], v[138:141], v[162:165], v[122:125]
	v_mfma_f32_16x16x32_bf16 v[110:113], v[130:133], v[170:173], v[110:113]
	v_mfma_f32_16x16x32_bf16 v[106:109], v[138:141], v[170:173], v[106:109]
	v_mfma_f32_16x16x32_bf16 v[94:97], v[130:133], v[194:197], v[94:97]
	v_mfma_f32_16x16x32_bf16 v[90:93], v[138:141], v[194:197], v[90:93]
	v_mfma_f32_16x16x32_bf16 v[78:81], v[130:133], v[202:205], v[78:81]
	v_mfma_f32_16x16x32_bf16 v[74:77], v[138:141], v[202:205], v[74:77]
	v_mfma_f32_16x16x32_bf16 v[126:129], v[134:137], v[166:169], v[126:129]
	v_mfma_f32_16x16x32_bf16 v[122:125], v[142:145], v[166:169], v[122:125]
	v_mfma_f32_16x16x32_bf16 v[110:113], v[134:137], v[174:177], v[110:113]
	v_mfma_f32_16x16x32_bf16 v[106:109], v[142:145], v[174:177], v[106:109]
	v_mfma_f32_16x16x32_bf16 v[94:97], v[134:137], v[198:201], v[94:97]
	v_mfma_f32_16x16x32_bf16 v[90:93], v[142:145], v[198:201], v[90:93]
	v_mfma_f32_16x16x32_bf16 v[78:81], v[134:137], v[212:215], v[78:81]
	v_mfma_f32_16x16x32_bf16 v[74:77], v[142:145], v[212:215], v[74:77]
	s_setprio 0
	s_setprio 1
	v_mfma_f32_16x16x32_bf16 v[118:121], v[146:149], v[162:165], v[118:121]
	v_mfma_f32_16x16x32_bf16 v[114:117], v[154:157], v[162:165], v[114:117]
	v_mfma_f32_16x16x32_bf16 v[102:105], v[146:149], v[170:173], v[102:105]
	v_mfma_f32_16x16x32_bf16 v[98:101], v[154:157], v[170:173], v[98:101]
	v_mfma_f32_16x16x32_bf16 v[86:89], v[146:149], v[194:197], v[86:89]
	v_mfma_f32_16x16x32_bf16 v[82:85], v[154:157], v[194:197], v[82:85]
	v_mfma_f32_16x16x32_bf16 v[70:73], v[146:149], v[202:205], v[70:73]
	v_mfma_f32_16x16x32_bf16 v[66:69], v[154:157], v[202:205], v[66:69]
	v_mfma_f32_16x16x32_bf16 v[118:121], v[150:153], v[166:169], v[118:121]
	v_mfma_f32_16x16x32_bf16 v[114:117], v[158:161], v[166:169], v[114:117]
	v_mfma_f32_16x16x32_bf16 v[102:105], v[150:153], v[174:177], v[102:105]
	v_mfma_f32_16x16x32_bf16 v[98:101], v[158:161], v[174:177], v[98:101]
	v_mfma_f32_16x16x32_bf16 v[86:89], v[150:153], v[198:201], v[86:89]
	v_mfma_f32_16x16x32_bf16 v[82:85], v[158:161], v[198:201], v[82:85]
	v_mfma_f32_16x16x32_bf16 v[70:73], v[150:153], v[212:215], v[70:73]
	v_mfma_f32_16x16x32_bf16 v[66:69], v[158:161], v[212:215], v[66:69]
	s_setprio 0
	s_barrier
	s_add_i32 s55, s49, s39
	v_lshl_add_u64 v[216:217], s[30:31], 0, v[180:181]
	s_mov_b32 m0, s55
	ds_read_b128 v[162:165], v210 offset:16384
	ds_read_b128 v[166:169], v210 offset:17408
	ds_read_b128 v[170:173], v210 offset:18432
	ds_read_b128 v[174:177], v210 offset:19456
	ds_read_b128 v[194:197], v210 offset:20480
	ds_read_b128 v[198:201], v210 offset:21504
	ds_read_b128 v[202:205], v210 offset:22528
	ds_read_b128 v[212:215], v210 offset:23552
	global_load_lds_dwordx4 v[216:217], off
	s_add_i32 m0, s55, 0x2000
	s_add_u32 s56, s30, 0x40000
	v_lshl_add_u64 v[218:219], s[30:31], 0, v[184:185]
	s_addc_u32 s57, s31, 0
	s_add_i32 s55, s50, s39
	global_load_lds_dwordx4 v[218:219], off
	v_lshl_add_u64 v[220:221], s[56:57], 0, v[180:181]
	s_mov_b32 m0, s55
	v_lshl_add_u64 v[222:223], s[34:35], 0, v[182:183]
	global_load_lds_dwordx4 v[220:221], off
	v_lshl_add_u64 v[220:221], s[56:57], 0, v[184:185]
	s_add_i32 m0, s55, 0x2000
	s_nop 0
	global_load_lds_dwordx4 v[220:221], off
	v_lshl_add_u64 v[220:221], s[34:35], 0, v[178:179]
	s_mov_b32 m0, s27
	s_nop 0
	global_load_lds_dwordx4 v[220:221], off
	s_mov_b32 m0, s40
	s_nop 0
	global_load_lds_dwordx4 v[222:223], off
	s_waitcnt vmcnt(8)
	s_waitcnt lgkmcnt(0)
	s_barrier
	s_setprio 1
	s_waitcnt lgkmcnt(0)
	v_mfma_f32_16x16x32_bf16 v[62:65], v[130:133], v[162:165], v[62:65]
	v_mfma_f32_16x16x32_bf16 v[58:61], v[138:141], v[162:165], v[58:61]
	v_mfma_f32_16x16x32_bf16 v[46:49], v[130:133], v[170:173], v[46:49]
	v_mfma_f32_16x16x32_bf16 v[42:45], v[138:141], v[170:173], v[42:45]
	v_mfma_f32_16x16x32_bf16 v[30:33], v[130:133], v[194:197], v[30:33]
	v_mfma_f32_16x16x32_bf16 v[26:29], v[138:141], v[194:197], v[26:29]
	v_mfma_f32_16x16x32_bf16 v[14:17], v[130:133], v[202:205], v[14:17]
	v_mfma_f32_16x16x32_bf16 v[10:13], v[138:141], v[202:205], v[10:13]
	v_mfma_f32_16x16x32_bf16 v[62:65], v[134:137], v[166:169], v[62:65]
	v_mfma_f32_16x16x32_bf16 v[58:61], v[142:145], v[166:169], v[58:61]
	v_mfma_f32_16x16x32_bf16 v[46:49], v[134:137], v[174:177], v[46:49]
	v_mfma_f32_16x16x32_bf16 v[42:45], v[142:145], v[174:177], v[42:45]
	v_mfma_f32_16x16x32_bf16 v[30:33], v[134:137], v[198:201], v[30:33]
	v_mfma_f32_16x16x32_bf16 v[26:29], v[142:145], v[198:201], v[26:29]
	v_mfma_f32_16x16x32_bf16 v[14:17], v[134:137], v[212:215], v[14:17]
	v_mfma_f32_16x16x32_bf16 v[10:13], v[142:145], v[212:215], v[10:13]
	s_setprio 0
	s_setprio 1
	v_mfma_f32_16x16x32_bf16 v[54:57], v[146:149], v[162:165], v[54:57]
	v_mfma_f32_16x16x32_bf16 v[50:53], v[154:157], v[162:165], v[50:53]
	v_mfma_f32_16x16x32_bf16 v[38:41], v[146:149], v[170:173], v[38:41]
	v_mfma_f32_16x16x32_bf16 v[34:37], v[154:157], v[170:173], v[34:37]
	v_mfma_f32_16x16x32_bf16 v[22:25], v[146:149], v[194:197], v[22:25]
	v_mfma_f32_16x16x32_bf16 v[18:21], v[154:157], v[194:197], v[18:21]
	v_mfma_f32_16x16x32_bf16 v[6:9], v[146:149], v[202:205], v[6:9]
	v_mfma_f32_16x16x32_bf16 v[2:5], v[154:157], v[202:205], v[2:5]
	v_mfma_f32_16x16x32_bf16 v[54:57], v[150:153], v[166:169], v[54:57]
	v_mfma_f32_16x16x32_bf16 v[50:53], v[158:161], v[166:169], v[50:53]
	v_mfma_f32_16x16x32_bf16 v[38:41], v[150:153], v[174:177], v[38:41]
	v_mfma_f32_16x16x32_bf16 v[34:37], v[158:161], v[174:177], v[34:37]
	v_mfma_f32_16x16x32_bf16 v[22:25], v[150:153], v[198:201], v[22:25]
	v_mfma_f32_16x16x32_bf16 v[18:21], v[158:161], v[198:201], v[18:21]
	v_mfma_f32_16x16x32_bf16 v[6:9], v[150:153], v[212:215], v[6:9]
	v_mfma_f32_16x16x32_bf16 v[2:5], v[158:161], v[212:215], v[2:5]
	s_setprio 0
	s_barrier
	s_add_i32 s55, 0, 0x18000
	s_add_i32 s56, 0, 0x1c000
	v_add_u32_e32 v142, s55, v206
	v_add_u32_e32 v158, s56, v206
	ds_read_b128 v[130:133], v142
	ds_read_b128 v[134:137], v142 offset:1024
	ds_read_b128 v[138:141], v142 offset:2048
	ds_read_b128 v[142:145], v142 offset:3072
	ds_read_b128 v[146:149], v158
	ds_read_b128 v[150:153], v158 offset:1024
	ds_read_b128 v[154:157], v158 offset:2048
	ds_read_b128 v[158:161], v158 offset:3072
	s_add_u32 s34, s34, 0x40000
	s_addc_u32 s35, s35, 0
	s_mov_b32 m0, s41
	v_lshl_add_u64 v[224:225], s[34:35], 0, v[178:179]
	ds_read_b128 v[162:165], v210 offset:32768
	ds_read_b128 v[166:169], v210 offset:33792
	ds_read_b128 v[170:173], v210 offset:34816
	ds_read_b128 v[174:177], v210 offset:35840
	ds_read_b128 v[194:197], v210 offset:36864
	ds_read_b128 v[198:201], v210 offset:37888
	ds_read_b128 v[202:205], v210 offset:38912
	ds_read_b128 v[212:215], v210 offset:39936
	global_load_lds_dwordx4 v[224:225], off
	v_lshl_add_u64 v[224:225], s[34:35], 0, v[182:183]
	s_mov_b32 m0, s42
	s_nop 0
	global_load_lds_dwordx4 v[224:225], off
	s_waitcnt vmcnt(8)
	s_waitcnt lgkmcnt(0)
	s_barrier
	s_setprio 1
	s_waitcnt lgkmcnt(0)
	v_mfma_f32_16x16x32_bf16 v[126:129], v[130:133], v[162:165], v[126:129]
	v_mfma_f32_16x16x32_bf16 v[122:125], v[138:141], v[162:165], v[122:125]
	v_mfma_f32_16x16x32_bf16 v[110:113], v[130:133], v[170:173], v[110:113]
	v_mfma_f32_16x16x32_bf16 v[106:109], v[138:141], v[170:173], v[106:109]
	v_mfma_f32_16x16x32_bf16 v[94:97], v[130:133], v[194:197], v[94:97]
	v_mfma_f32_16x16x32_bf16 v[90:93], v[138:141], v[194:197], v[90:93]
	v_mfma_f32_16x16x32_bf16 v[78:81], v[130:133], v[202:205], v[78:81]
	v_mfma_f32_16x16x32_bf16 v[74:77], v[138:141], v[202:205], v[74:77]
	v_mfma_f32_16x16x32_bf16 v[126:129], v[134:137], v[166:169], v[126:129]
	v_mfma_f32_16x16x32_bf16 v[122:125], v[142:145], v[166:169], v[122:125]
	v_mfma_f32_16x16x32_bf16 v[110:113], v[134:137], v[174:177], v[110:113]
	v_mfma_f32_16x16x32_bf16 v[106:109], v[142:145], v[174:177], v[106:109]
	v_mfma_f32_16x16x32_bf16 v[94:97], v[134:137], v[198:201], v[94:97]
	v_mfma_f32_16x16x32_bf16 v[90:93], v[142:145], v[198:201], v[90:93]
	v_mfma_f32_16x16x32_bf16 v[78:81], v[134:137], v[212:215], v[78:81]
	v_mfma_f32_16x16x32_bf16 v[74:77], v[142:145], v[212:215], v[74:77]
	s_setprio 0
	s_setprio 1
	v_mfma_f32_16x16x32_bf16 v[118:121], v[146:149], v[162:165], v[118:121]
	v_mfma_f32_16x16x32_bf16 v[114:117], v[154:157], v[162:165], v[114:117]
	v_mfma_f32_16x16x32_bf16 v[102:105], v[146:149], v[170:173], v[102:105]
	v_mfma_f32_16x16x32_bf16 v[98:101], v[154:157], v[170:173], v[98:101]
	v_mfma_f32_16x16x32_bf16 v[86:89], v[146:149], v[194:197], v[86:89]
	v_mfma_f32_16x16x32_bf16 v[82:85], v[154:157], v[194:197], v[82:85]
	v_mfma_f32_16x16x32_bf16 v[70:73], v[146:149], v[202:205], v[70:73]
	v_mfma_f32_16x16x32_bf16 v[66:69], v[154:157], v[202:205], v[66:69]
	v_mfma_f32_16x16x32_bf16 v[118:121], v[150:153], v[166:169], v[118:121]
	v_mfma_f32_16x16x32_bf16 v[114:117], v[158:161], v[166:169], v[114:117]
	v_mfma_f32_16x16x32_bf16 v[102:105], v[150:153], v[174:177], v[102:105]
	v_mfma_f32_16x16x32_bf16 v[98:101], v[158:161], v[174:177], v[98:101]
	v_mfma_f32_16x16x32_bf16 v[86:89], v[150:153], v[198:201], v[86:89]
	v_mfma_f32_16x16x32_bf16 v[82:85], v[158:161], v[198:201], v[82:85]
	v_mfma_f32_16x16x32_bf16 v[70:73], v[150:153], v[212:215], v[70:73]
	v_mfma_f32_16x16x32_bf16 v[66:69], v[158:161], v[212:215], v[66:69]
	s_setprio 0
	s_barrier
	s_add_i32 s34, s55, s39
	v_lshl_add_u64 v[216:217], v[216:217], 0, s[12:13]
	s_mov_b32 m0, s34
	ds_read_b128 v[162:165], v210 offset:49152
	ds_read_b128 v[166:169], v210 offset:50176
	ds_read_b128 v[170:173], v210 offset:51200
	ds_read_b128 v[174:177], v210 offset:52224
	ds_read_b128 v[194:197], v210 offset:53248
	ds_read_b128 v[198:201], v210 offset:54272
	ds_read_b128 v[202:205], v210 offset:55296
	ds_read_b128 v[212:215], v210 offset:56320
	global_load_lds_dwordx4 v[216:217], off
	s_add_i32 m0, s34, 0x2000
	s_add_u32 s30, s30, 0x40080
	v_lshl_add_u64 v[216:217], v[218:219], 0, s[12:13]
	s_addc_u32 s31, s31, 0
	s_add_i32 s34, s56, s39
	global_load_lds_dwordx4 v[216:217], off
	v_lshl_add_u64 v[216:217], s[30:31], 0, v[180:181]
	s_mov_b32 m0, s34
	s_nop 0
	global_load_lds_dwordx4 v[216:217], off
	v_lshl_add_u64 v[216:217], s[30:31], 0, v[184:185]
	s_add_i32 m0, s34, 0x2000
	s_nop 0
	global_load_lds_dwordx4 v[216:217], off
	v_lshl_add_u64 v[216:217], v[220:221], 0, s[12:13]
	s_mov_b32 m0, s44
	s_nop 0
	global_load_lds_dwordx4 v[216:217], off
	v_lshl_add_u64 v[216:217], v[222:223], 0, s[12:13]
	s_mov_b32 m0, s45
	s_nop 0
	global_load_lds_dwordx4 v[216:217], off
	s_waitcnt vmcnt(8)
	s_waitcnt lgkmcnt(0)
	s_barrier
	s_setprio 1
	s_waitcnt lgkmcnt(0)
	v_mfma_f32_16x16x32_bf16 v[62:65], v[130:133], v[162:165], v[62:65]
	v_mfma_f32_16x16x32_bf16 v[58:61], v[138:141], v[162:165], v[58:61]
	v_mfma_f32_16x16x32_bf16 v[46:49], v[130:133], v[170:173], v[46:49]
	v_mfma_f32_16x16x32_bf16 v[42:45], v[138:141], v[170:173], v[42:45]
	v_mfma_f32_16x16x32_bf16 v[30:33], v[130:133], v[194:197], v[30:33]
	v_mfma_f32_16x16x32_bf16 v[26:29], v[138:141], v[194:197], v[26:29]
	v_mfma_f32_16x16x32_bf16 v[14:17], v[130:133], v[202:205], v[14:17]
	v_mfma_f32_16x16x32_bf16 v[10:13], v[138:141], v[202:205], v[10:13]
	v_mfma_f32_16x16x32_bf16 v[62:65], v[134:137], v[166:169], v[62:65]
	v_mfma_f32_16x16x32_bf16 v[58:61], v[142:145], v[166:169], v[58:61]
	v_mfma_f32_16x16x32_bf16 v[46:49], v[134:137], v[174:177], v[46:49]
	v_mfma_f32_16x16x32_bf16 v[42:45], v[142:145], v[174:177], v[42:45]
	v_mfma_f32_16x16x32_bf16 v[30:33], v[134:137], v[198:201], v[30:33]
	v_mfma_f32_16x16x32_bf16 v[26:29], v[142:145], v[198:201], v[26:29]
	v_mfma_f32_16x16x32_bf16 v[14:17], v[134:137], v[212:215], v[14:17]
	v_mfma_f32_16x16x32_bf16 v[10:13], v[142:145], v[212:215], v[10:13]
	s_setprio 0
	s_setprio 1
	s_add_i32 s54, s54, 2
	s_add_u32 s28, s28, 0x100
	s_addc_u32 s29, s29, 0
	s_add_u32 s52, s52, 0x100
	s_addc_u32 s53, s53, 0
	s_cmp_gt_u32 s54, 13
	v_mfma_f32_16x16x32_bf16 v[54:57], v[146:149], v[162:165], v[54:57]
	v_mfma_f32_16x16x32_bf16 v[50:53], v[154:157], v[162:165], v[50:53]
	v_mfma_f32_16x16x32_bf16 v[38:41], v[146:149], v[170:173], v[38:41]
	v_mfma_f32_16x16x32_bf16 v[34:37], v[154:157], v[170:173], v[34:37]
	v_mfma_f32_16x16x32_bf16 v[22:25], v[146:149], v[194:197], v[22:25]
	v_mfma_f32_16x16x32_bf16 v[18:21], v[154:157], v[194:197], v[18:21]
	v_mfma_f32_16x16x32_bf16 v[6:9], v[146:149], v[202:205], v[6:9]
	v_mfma_f32_16x16x32_bf16 v[2:5], v[154:157], v[202:205], v[2:5]
	v_mfma_f32_16x16x32_bf16 v[54:57], v[150:153], v[166:169], v[54:57]
	v_mfma_f32_16x16x32_bf16 v[50:53], v[158:161], v[166:169], v[50:53]
	v_mfma_f32_16x16x32_bf16 v[38:41], v[150:153], v[174:177], v[38:41]
	v_mfma_f32_16x16x32_bf16 v[34:37], v[158:161], v[174:177], v[34:37]
	v_mfma_f32_16x16x32_bf16 v[22:25], v[150:153], v[198:201], v[22:25]
	v_mfma_f32_16x16x32_bf16 v[18:21], v[158:161], v[198:201], v[18:21]
	v_mfma_f32_16x16x32_bf16 v[6:9], v[150:153], v[212:215], v[6:9]
	v_mfma_f32_16x16x32_bf16 v[2:5], v[158:161], v[212:215], v[2:5]
	s_setprio 0
	s_barrier
	s_cbranch_scc0 .LBB0_845
	s_and_b64 vcc, exec, s[14:15]
	s_cbranch_vccz .LBB0_848
	s_barrier

.LBB0_956:
	ds_read_b128 v[146:149], v158
	ds_read_b128 v[150:153], v158 offset:1024
	ds_read_b128 v[164:167], v158 offset:2048
	ds_read_b128 v[168:171], v158 offset:3072
	ds_read_b128 v[172:175], v159
	ds_read_b128 v[176:179], v159 offset:1024
	ds_read_b128 v[180:183], v159 offset:2048
	ds_read_b128 v[184:187], v159 offset:3072
	s_add_u32 s36, s6, 0xfffc0080
	s_addc_u32 s37, s7, -1
	s_cmp_eq_u32 s65, 12
	s_cselect_b32 s39, s29, s37
	s_cselect_b32 s38, s61, s36
	s_cselect_b32 s37, s27, s64
	s_cselect_b32 s36, s62, s63
	v_lshl_add_u64 v[154:155], s[6:7], 0, v[138:139]
	s_add_i32 m0, s45, 0xc000
	ds_read_b128 v[188:191], v160
	ds_read_b128 v[192:195], v160 offset:1024
	ds_read_b128 v[196:199], v160 offset:2048
	ds_read_b128 v[200:203], v160 offset:3072
	ds_read_b128 v[204:207], v160 offset:4096
	ds_read_b128 v[208:211], v160 offset:5120
	ds_read_b128 v[212:215], v160 offset:6144
	ds_read_b128 v[216:219], v160 offset:7168
	global_load_lds_dwordx4 v[154:155], off
	v_lshl_add_u64 v[154:155], s[6:7], 0, v[140:141]
	s_add_i32 m0, s45, 0xe000
	s_nop 0
	global_load_lds_dwordx4 v[154:155], off
	s_waitcnt vmcnt(8)
	s_waitcnt lgkmcnt(0)
	s_barrier
	s_setprio 1
	s_waitcnt lgkmcnt(0)
	v_mfma_f32_16x16x32_bf16 v[126:129], v[146:149], v[188:191], v[126:129]
	v_mfma_f32_16x16x32_bf16 v[122:125], v[164:167], v[188:191], v[122:125]
	v_mfma_f32_16x16x32_bf16 v[110:113], v[146:149], v[196:199], v[110:113]
	v_mfma_f32_16x16x32_bf16 v[106:109], v[164:167], v[196:199], v[106:109]
	v_mfma_f32_16x16x32_bf16 v[94:97], v[146:149], v[204:207], v[94:97]
	v_mfma_f32_16x16x32_bf16 v[90:93], v[164:167], v[204:207], v[90:93]
	v_mfma_f32_16x16x32_bf16 v[78:81], v[146:149], v[212:215], v[78:81]
	v_mfma_f32_16x16x32_bf16 v[74:77], v[164:167], v[212:215], v[74:77]
	v_mfma_f32_16x16x32_bf16 v[126:129], v[150:153], v[192:195], v[126:129]
	v_mfma_f32_16x16x32_bf16 v[122:125], v[168:171], v[192:195], v[122:125]
	v_mfma_f32_16x16x32_bf16 v[110:113], v[150:153], v[200:203], v[110:113]
	v_mfma_f32_16x16x32_bf16 v[106:109], v[168:171], v[200:203], v[106:109]
	v_mfma_f32_16x16x32_bf16 v[94:97], v[150:153], v[208:211], v[94:97]
	v_mfma_f32_16x16x32_bf16 v[90:93], v[168:171], v[208:211], v[90:93]
	v_mfma_f32_16x16x32_bf16 v[78:81], v[150:153], v[216:219], v[78:81]
	v_mfma_f32_16x16x32_bf16 v[74:77], v[168:171], v[216:219], v[74:77]
	s_setprio 0
	s_setprio 1
	v_mfma_f32_16x16x32_bf16 v[118:121], v[172:175], v[188:191], v[118:121]
	v_mfma_f32_16x16x32_bf16 v[114:117], v[180:183], v[188:191], v[114:117]
	v_mfma_f32_16x16x32_bf16 v[102:105], v[172:175], v[196:199], v[102:105]
	v_mfma_f32_16x16x32_bf16 v[98:101], v[180:183], v[196:199], v[98:101]
	v_mfma_f32_16x16x32_bf16 v[86:89], v[172:175], v[204:207], v[86:89]
	v_mfma_f32_16x16x32_bf16 v[82:85], v[180:183], v[204:207], v[82:85]
	v_mfma_f32_16x16x32_bf16 v[70:73], v[172:175], v[212:215], v[70:73]
	v_mfma_f32_16x16x32_bf16 v[66:69], v[180:183], v[212:215], v[66:69]
	v_mfma_f32_16x16x32_bf16 v[118:121], v[176:179], v[192:195], v[118:121]
	v_mfma_f32_16x16x32_bf16 v[114:117], v[184:187], v[192:195], v[114:117]
	v_mfma_f32_16x16x32_bf16 v[102:105], v[176:179], v[200:203], v[102:105]
	v_mfma_f32_16x16x32_bf16 v[98:101], v[184:187], v[200:203], v[98:101]
	v_mfma_f32_16x16x32_bf16 v[86:89], v[176:179], v[208:211], v[86:89]
	v_mfma_f32_16x16x32_bf16 v[82:85], v[184:187], v[208:211], v[82:85]
	v_mfma_f32_16x16x32_bf16 v[70:73], v[176:179], v[216:219], v[70:73]
	v_mfma_f32_16x16x32_bf16 v[66:69], v[184:187], v[216:219], v[66:69]
	s_setprio 0
	s_barrier
	s_add_i32 s66, s54, s44
	v_lshl_add_u64 v[154:155], s[36:37], 0, v[132:133]
	s_mov_b32 m0, s66
	ds_read_b128 v[188:191], v160 offset:16384
	ds_read_b128 v[192:195], v160 offset:17408
	ds_read_b128 v[196:199], v160 offset:18432
	ds_read_b128 v[200:203], v160 offset:19456
	ds_read_b128 v[204:207], v160 offset:20480
	ds_read_b128 v[208:211], v160 offset:21504
	ds_read_b128 v[212:215], v160 offset:22528
	ds_read_b128 v[216:219], v160 offset:23552
	global_load_lds_dwordx4 v[154:155], off
	s_add_i32 m0, s66, 0x2000
	s_add_u32 s66, s36, 0x40000
	v_lshl_add_u64 v[220:221], s[36:37], 0, v[136:137]
	s_addc_u32 s67, s37, 0
	s_add_i32 s68, s55, s44
	global_load_lds_dwordx4 v[220:221], off
	v_lshl_add_u64 v[222:223], s[66:67], 0, v[132:133]
	s_mov_b32 m0, s68
	v_lshl_add_u64 v[224:225], s[38:39], 0, v[134:135]
	global_load_lds_dwordx4 v[222:223], off
	v_lshl_add_u64 v[222:223], s[66:67], 0, v[136:137]
	s_add_i32 m0, s68, 0x2000
	s_nop 0
	global_load_lds_dwordx4 v[222:223], off
	v_lshl_add_u64 v[222:223], s[38:39], 0, v[130:131]
	s_mov_b32 m0, s45
	s_nop 0
	global_load_lds_dwordx4 v[222:223], off
	s_mov_b32 m0, s46
	s_nop 0
	global_load_lds_dwordx4 v[224:225], off
	s_waitcnt vmcnt(8)
	s_waitcnt lgkmcnt(0)
	s_barrier
	s_setprio 1
	s_waitcnt lgkmcnt(0)
	v_mfma_f32_16x16x32_bf16 v[62:65], v[146:149], v[188:191], v[62:65]
	v_mfma_f32_16x16x32_bf16 v[58:61], v[164:167], v[188:191], v[58:61]
	v_mfma_f32_16x16x32_bf16 v[46:49], v[146:149], v[196:199], v[46:49]
	v_mfma_f32_16x16x32_bf16 v[42:45], v[164:167], v[196:199], v[42:45]
	v_mfma_f32_16x16x32_bf16 v[30:33], v[146:149], v[204:207], v[30:33]
	v_mfma_f32_16x16x32_bf16 v[26:29], v[164:167], v[204:207], v[26:29]
	v_mfma_f32_16x16x32_bf16 v[14:17], v[146:149], v[212:215], v[14:17]
	v_mfma_f32_16x16x32_bf16 v[10:13], v[164:167], v[212:215], v[10:13]
	v_mfma_f32_16x16x32_bf16 v[62:65], v[150:153], v[192:195], v[62:65]
	v_mfma_f32_16x16x32_bf16 v[58:61], v[168:171], v[192:195], v[58:61]
	v_mfma_f32_16x16x32_bf16 v[46:49], v[150:153], v[200:203], v[46:49]
	v_mfma_f32_16x16x32_bf16 v[42:45], v[168:171], v[200:203], v[42:45]
	v_mfma_f32_16x16x32_bf16 v[30:33], v[150:153], v[208:211], v[30:33]
	v_mfma_f32_16x16x32_bf16 v[26:29], v[168:171], v[208:211], v[26:29]
	v_mfma_f32_16x16x32_bf16 v[14:17], v[150:153], v[216:219], v[14:17]
	v_mfma_f32_16x16x32_bf16 v[10:13], v[168:171], v[216:219], v[10:13]
	s_setprio 0
	s_setprio 1
	v_mfma_f32_16x16x32_bf16 v[54:57], v[172:175], v[188:191], v[54:57]
	v_mfma_f32_16x16x32_bf16 v[50:53], v[180:183], v[188:191], v[50:53]
	v_mfma_f32_16x16x32_bf16 v[38:41], v[172:175], v[196:199], v[38:41]
	v_mfma_f32_16x16x32_bf16 v[34:37], v[180:183], v[196:199], v[34:37]
	v_mfma_f32_16x16x32_bf16 v[22:25], v[172:175], v[204:207], v[22:25]
	v_mfma_f32_16x16x32_bf16 v[18:21], v[180:183], v[204:207], v[18:21]
	v_mfma_f32_16x16x32_bf16 v[6:9], v[172:175], v[212:215], v[6:9]
	v_mfma_f32_16x16x32_bf16 v[2:5], v[180:183], v[212:215], v[2:5]
	v_mfma_f32_16x16x32_bf16 v[54:57], v[176:179], v[192:195], v[54:57]
	v_mfma_f32_16x16x32_bf16 v[50:53], v[184:187], v[192:195], v[50:53]
	v_mfma_f32_16x16x32_bf16 v[38:41], v[176:179], v[200:203], v[38:41]
	v_mfma_f32_16x16x32_bf16 v[34:37], v[184:187], v[200:203], v[34:37]
	v_mfma_f32_16x16x32_bf16 v[22:25], v[176:179], v[208:211], v[22:25]
	v_mfma_f32_16x16x32_bf16 v[18:21], v[184:187], v[208:211], v[18:21]
	v_mfma_f32_16x16x32_bf16 v[6:9], v[176:179], v[216:219], v[6:9]
	v_mfma_f32_16x16x32_bf16 v[2:5], v[184:187], v[216:219], v[2:5]
	s_setprio 0
	s_barrier
	s_add_i32 s66, 0, 0x18000
	v_add_u32_e32 v163, s66, v156
	s_add_i32 s67, 0, 0x1c000
	ds_read_b128 v[146:149], v163
	ds_read_b128 v[150:153], v163 offset:1024
	ds_read_b128 v[164:167], v163 offset:2048
	ds_read_b128 v[168:171], v163 offset:3072
	v_add_u32_e32 v163, s67, v156
	ds_read_b128 v[172:175], v163
	ds_read_b128 v[176:179], v163 offset:1024
	ds_read_b128 v[180:183], v163 offset:2048
	ds_read_b128 v[184:187], v163 offset:3072
	s_add_u32 s38, s38, 0x40000
	s_addc_u32 s39, s39, 0
	s_mov_b32 m0, s47
	v_lshl_add_u64 v[228:229], s[38:39], 0, v[130:131]
	ds_read_b128 v[188:191], v160 offset:32768
	ds_read_b128 v[192:195], v160 offset:33792
	ds_read_b128 v[196:199], v160 offset:34816
	ds_read_b128 v[200:203], v160 offset:35840
	ds_read_b128 v[204:207], v160 offset:36864
	ds_read_b128 v[208:211], v160 offset:37888
	ds_read_b128 v[212:215], v160 offset:38912
	ds_read_b128 v[216:219], v160 offset:39936
	global_load_lds_dwordx4 v[228:229], off
	v_lshl_add_u64 v[228:229], s[38:39], 0, v[134:135]
	s_mov_b32 m0, s48
	s_nop 0
	global_load_lds_dwordx4 v[228:229], off
	s_waitcnt vmcnt(8)
	s_waitcnt lgkmcnt(0)
	s_barrier
	s_setprio 1
	s_waitcnt lgkmcnt(0)
	v_mfma_f32_16x16x32_bf16 v[126:129], v[146:149], v[188:191], v[126:129]
	v_mfma_f32_16x16x32_bf16 v[122:125], v[164:167], v[188:191], v[122:125]
	v_mfma_f32_16x16x32_bf16 v[110:113], v[146:149], v[196:199], v[110:113]
	v_mfma_f32_16x16x32_bf16 v[106:109], v[164:167], v[196:199], v[106:109]
	v_mfma_f32_16x16x32_bf16 v[94:97], v[146:149], v[204:207], v[94:97]
	v_mfma_f32_16x16x32_bf16 v[90:93], v[164:167], v[204:207], v[90:93]
	v_mfma_f32_16x16x32_bf16 v[78:81], v[146:149], v[212:215], v[78:81]
	v_mfma_f32_16x16x32_bf16 v[74:77], v[164:167], v[212:215], v[74:77]
	v_mfma_f32_16x16x32_bf16 v[126:129], v[150:153], v[192:195], v[126:129]
	v_mfma_f32_16x16x32_bf16 v[122:125], v[168:171], v[192:195], v[122:125]
	v_mfma_f32_16x16x32_bf16 v[110:113], v[150:153], v[200:203], v[110:113]
	v_mfma_f32_16x16x32_bf16 v[106:109], v[168:171], v[200:203], v[106:109]
	v_mfma_f32_16x16x32_bf16 v[94:97], v[150:153], v[208:211], v[94:97]
	v_mfma_f32_16x16x32_bf16 v[90:93], v[168:171], v[208:211], v[90:93]
	v_mfma_f32_16x16x32_bf16 v[78:81], v[150:153], v[216:219], v[78:81]
	v_mfma_f32_16x16x32_bf16 v[74:77], v[168:171], v[216:219], v[74:77]
	s_setprio 0
	s_setprio 1
	v_mfma_f32_16x16x32_bf16 v[118:121], v[172:175], v[188:191], v[118:121]
	v_mfma_f32_16x16x32_bf16 v[114:117], v[180:183], v[188:191], v[114:117]
	v_mfma_f32_16x16x32_bf16 v[102:105], v[172:175], v[196:199], v[102:105]
	v_mfma_f32_16x16x32_bf16 v[98:101], v[180:183], v[196:199], v[98:101]
	v_mfma_f32_16x16x32_bf16 v[86:89], v[172:175], v[204:207], v[86:89]
	v_mfma_f32_16x16x32_bf16 v[82:85], v[180:183], v[204:207], v[82:85]
	v_mfma_f32_16x16x32_bf16 v[70:73], v[172:175], v[212:215], v[70:73]
	v_mfma_f32_16x16x32_bf16 v[66:69], v[180:183], v[212:215], v[66:69]
	v_mfma_f32_16x16x32_bf16 v[118:121], v[176:179], v[192:195], v[118:121]
	v_mfma_f32_16x16x32_bf16 v[114:117], v[184:187], v[192:195], v[114:117]
	v_mfma_f32_16x16x32_bf16 v[102:105], v[176:179], v[200:203], v[102:105]
	v_mfma_f32_16x16x32_bf16 v[98:101], v[184:187], v[200:203], v[98:101]
	v_mfma_f32_16x16x32_bf16 v[86:89], v[176:179], v[208:211], v[86:89]
	v_mfma_f32_16x16x32_bf16 v[82:85], v[184:187], v[208:211], v[82:85]
	v_mfma_f32_16x16x32_bf16 v[70:73], v[176:179], v[216:219], v[70:73]
	v_mfma_f32_16x16x32_bf16 v[66:69], v[184:187], v[216:219], v[66:69]
	s_setprio 0
	s_barrier
	s_add_i32 s38, s66, s44
	v_lshl_add_u64 v[154:155], v[154:155], 0, s[10:11]
	s_mov_b32 m0, s38
	ds_read_b128 v[188:191], v160 offset:49152
	ds_read_b128 v[192:195], v160 offset:50176
	ds_read_b128 v[196:199], v160 offset:51200
	ds_read_b128 v[200:203], v160 offset:52224
	ds_read_b128 v[204:207], v160 offset:53248
	ds_read_b128 v[208:211], v160 offset:54272
	ds_read_b128 v[212:215], v160 offset:55296
	ds_read_b128 v[216:219], v160 offset:56320
	global_load_lds_dwordx4 v[154:155], off
	s_add_i32 m0, s38, 0x2000
	s_add_u32 s36, s36, 0x40080
	v_lshl_add_u64 v[154:155], v[220:221], 0, s[10:11]
	s_addc_u32 s37, s37, 0
	s_add_i32 s38, s67, s44
	global_load_lds_dwordx4 v[154:155], off
	v_lshl_add_u64 v[154:155], s[36:37], 0, v[132:133]
	s_mov_b32 m0, s38
	s_nop 0
	global_load_lds_dwordx4 v[154:155], off
	v_lshl_add_u64 v[154:155], s[36:37], 0, v[136:137]
	s_add_i32 m0, s38, 0x2000
	s_nop 0
	global_load_lds_dwordx4 v[154:155], off
	v_lshl_add_u64 v[154:155], v[222:223], 0, s[10:11]
	s_mov_b32 m0, s50
	s_nop 0
	global_load_lds_dwordx4 v[154:155], off
	v_lshl_add_u64 v[154:155], v[224:225], 0, s[10:11]
	s_mov_b32 m0, s51
	s_nop 0
	global_load_lds_dwordx4 v[154:155], off
	s_waitcnt vmcnt(8)
	s_waitcnt lgkmcnt(0)
	s_barrier
	s_setprio 1
	s_waitcnt lgkmcnt(0)
	v_mfma_f32_16x16x32_bf16 v[62:65], v[146:149], v[188:191], v[62:65]
	v_mfma_f32_16x16x32_bf16 v[58:61], v[164:167], v[188:191], v[58:61]
	v_mfma_f32_16x16x32_bf16 v[46:49], v[146:149], v[196:199], v[46:49]
	v_mfma_f32_16x16x32_bf16 v[42:45], v[164:167], v[196:199], v[42:45]
	v_mfma_f32_16x16x32_bf16 v[30:33], v[146:149], v[204:207], v[30:33]
	v_mfma_f32_16x16x32_bf16 v[26:29], v[164:167], v[204:207], v[26:29]
	v_mfma_f32_16x16x32_bf16 v[14:17], v[146:149], v[212:215], v[14:17]
	v_mfma_f32_16x16x32_bf16 v[10:13], v[164:167], v[212:215], v[10:13]
	v_mfma_f32_16x16x32_bf16 v[62:65], v[150:153], v[192:195], v[62:65]
	v_mfma_f32_16x16x32_bf16 v[58:61], v[168:171], v[192:195], v[58:61]
	v_mfma_f32_16x16x32_bf16 v[46:49], v[150:153], v[200:203], v[46:49]
	v_mfma_f32_16x16x32_bf16 v[42:45], v[168:171], v[200:203], v[42:45]
	v_mfma_f32_16x16x32_bf16 v[30:33], v[150:153], v[208:211], v[30:33]
	v_mfma_f32_16x16x32_bf16 v[26:29], v[168:171], v[208:211], v[26:29]
	v_mfma_f32_16x16x32_bf16 v[14:17], v[150:153], v[216:219], v[14:17]
	v_mfma_f32_16x16x32_bf16 v[10:13], v[168:171], v[216:219], v[10:13]
	s_setprio 0
	s_setprio 1
	s_add_i32 s65, s65, 2
	s_add_u32 s6, s6, 0x100
	s_addc_u32 s7, s7, 0
	s_add_u32 s63, s63, 0x100
	s_addc_u32 s64, s64, 0
	s_cmp_gt_u32 s65, 13
	v_mfma_f32_16x16x32_bf16 v[54:57], v[172:175], v[188:191], v[54:57]
	v_mfma_f32_16x16x32_bf16 v[50:53], v[180:183], v[188:191], v[50:53]
	v_mfma_f32_16x16x32_bf16 v[38:41], v[172:175], v[196:199], v[38:41]
	v_mfma_f32_16x16x32_bf16 v[34:37], v[180:183], v[196:199], v[34:37]
	v_mfma_f32_16x16x32_bf16 v[22:25], v[172:175], v[204:207], v[22:25]
	v_mfma_f32_16x16x32_bf16 v[18:21], v[180:183], v[204:207], v[18:21]
	v_mfma_f32_16x16x32_bf16 v[6:9], v[172:175], v[212:215], v[6:9]
	v_mfma_f32_16x16x32_bf16 v[2:5], v[180:183], v[212:215], v[2:5]
	v_mfma_f32_16x16x32_bf16 v[54:57], v[176:179], v[192:195], v[54:57]
	v_mfma_f32_16x16x32_bf16 v[50:53], v[184:187], v[192:195], v[50:53]
	v_mfma_f32_16x16x32_bf16 v[38:41], v[176:179], v[200:203], v[38:41]
	v_mfma_f32_16x16x32_bf16 v[34:37], v[184:187], v[200:203], v[34:37]
	v_mfma_f32_16x16x32_bf16 v[22:25], v[176:179], v[208:211], v[22:25]
	v_mfma_f32_16x16x32_bf16 v[18:21], v[184:187], v[208:211], v[18:21]
	v_mfma_f32_16x16x32_bf16 v[6:9], v[176:179], v[216:219], v[6:9]
	v_mfma_f32_16x16x32_bf16 v[2:5], v[184:187], v[216:219], v[2:5]
	s_setprio 0
	s_barrier
	s_cbranch_scc0 .LBB0_956
	s_and_b64 vcc, exec, s[12:13]
	s_cbranch_vccz .LBB0_959
	s_barrier

.LBB0_1051:
	ds_read_b128 v[144:147], v155
	ds_read_b128 v[148:151], v155 offset:1024
	ds_read_b128 v[158:161], v155 offset:2048
	ds_read_b128 v[162:165], v155 offset:3072
	ds_read_b128 v[166:169], v156
	ds_read_b128 v[170:173], v156 offset:1024
	ds_read_b128 v[174:177], v156 offset:2048
	ds_read_b128 v[178:181], v156 offset:3072
	s_add_u32 s22, s20, 0xfff00080
	s_addc_u32 s23, s21, -1
	s_cmp_eq_u32 s47, 60
	s_cselect_b32 s25, s13, s23
	s_cselect_b32 s24, s43, s22
	s_cselect_b32 s23, s11, s46
	s_cselect_b32 s22, s44, s45
	v_lshl_add_u64 v[214:215], s[20:21], 0, v[136:137]
	s_add_i32 m0, s19, 0xc000
	ds_read_b128 v[182:185], v157
	ds_read_b128 v[186:189], v157 offset:1024
	ds_read_b128 v[190:193], v157 offset:2048
	ds_read_b128 v[194:197], v157 offset:3072
	ds_read_b128 v[198:201], v157 offset:4096
	ds_read_b128 v[202:205], v157 offset:5120
	ds_read_b128 v[206:209], v157 offset:6144
	ds_read_b128 v[210:213], v157 offset:7168
	global_load_lds_dwordx4 v[214:215], off
	v_lshl_add_u64 v[214:215], s[20:21], 0, v[138:139]
	s_add_i32 m0, s19, 0xe000
	s_nop 0
	global_load_lds_dwordx4 v[214:215], off
	s_waitcnt vmcnt(8)
	s_waitcnt lgkmcnt(0)
	s_barrier
	s_setprio 1
	s_waitcnt lgkmcnt(0)
	v_mfma_f32_16x16x32_bf16 v[124:127], v[144:147], v[182:185], v[124:127]
	v_mfma_f32_16x16x32_bf16 v[120:123], v[158:161], v[182:185], v[120:123]
	v_mfma_f32_16x16x32_bf16 v[108:111], v[144:147], v[190:193], v[108:111]
	v_mfma_f32_16x16x32_bf16 v[104:107], v[158:161], v[190:193], v[104:107]
	v_mfma_f32_16x16x32_bf16 v[92:95], v[144:147], v[198:201], v[92:95]
	v_mfma_f32_16x16x32_bf16 v[88:91], v[158:161], v[198:201], v[88:91]
	v_mfma_f32_16x16x32_bf16 v[76:79], v[144:147], v[206:209], v[76:79]
	v_mfma_f32_16x16x32_bf16 v[72:75], v[158:161], v[206:209], v[72:75]
	v_mfma_f32_16x16x32_bf16 v[124:127], v[148:151], v[186:189], v[124:127]
	v_mfma_f32_16x16x32_bf16 v[120:123], v[162:165], v[186:189], v[120:123]
	v_mfma_f32_16x16x32_bf16 v[108:111], v[148:151], v[194:197], v[108:111]
	v_mfma_f32_16x16x32_bf16 v[104:107], v[162:165], v[194:197], v[104:107]
	v_mfma_f32_16x16x32_bf16 v[92:95], v[148:151], v[202:205], v[92:95]
	v_mfma_f32_16x16x32_bf16 v[88:91], v[162:165], v[202:205], v[88:91]
	v_mfma_f32_16x16x32_bf16 v[76:79], v[148:151], v[210:213], v[76:79]
	v_mfma_f32_16x16x32_bf16 v[72:75], v[162:165], v[210:213], v[72:75]
	s_setprio 0
	s_setprio 1
	v_mfma_f32_16x16x32_bf16 v[116:119], v[166:169], v[182:185], v[116:119]
	v_mfma_f32_16x16x32_bf16 v[112:115], v[174:177], v[182:185], v[112:115]
	v_mfma_f32_16x16x32_bf16 v[100:103], v[166:169], v[190:193], v[100:103]
	v_mfma_f32_16x16x32_bf16 v[96:99], v[174:177], v[190:193], v[96:99]
	v_mfma_f32_16x16x32_bf16 v[84:87], v[166:169], v[198:201], v[84:87]
	v_mfma_f32_16x16x32_bf16 v[80:83], v[174:177], v[198:201], v[80:83]
	v_mfma_f32_16x16x32_bf16 v[68:71], v[166:169], v[206:209], v[68:71]
	v_mfma_f32_16x16x32_bf16 v[64:67], v[174:177], v[206:209], v[64:67]
	v_mfma_f32_16x16x32_bf16 v[116:119], v[170:173], v[186:189], v[116:119]
	v_mfma_f32_16x16x32_bf16 v[112:115], v[178:181], v[186:189], v[112:115]
	v_mfma_f32_16x16x32_bf16 v[100:103], v[170:173], v[194:197], v[100:103]
	v_mfma_f32_16x16x32_bf16 v[96:99], v[178:181], v[194:197], v[96:99]
	v_mfma_f32_16x16x32_bf16 v[84:87], v[170:173], v[202:205], v[84:87]
	v_mfma_f32_16x16x32_bf16 v[80:83], v[178:181], v[202:205], v[80:83]
	v_mfma_f32_16x16x32_bf16 v[68:71], v[170:173], v[210:213], v[68:71]
	v_mfma_f32_16x16x32_bf16 v[64:67], v[178:181], v[210:213], v[64:67]
	s_setprio 0
	s_barrier
	s_add_i32 s48, s40, s31
	v_lshl_add_u64 v[214:215], s[22:23], 0, v[130:131]
	s_mov_b32 m0, s48
	ds_read_b128 v[182:185], v157 offset:16384
	ds_read_b128 v[186:189], v157 offset:17408
	ds_read_b128 v[190:193], v157 offset:18432
	ds_read_b128 v[194:197], v157 offset:19456
	ds_read_b128 v[198:201], v157 offset:20480
	ds_read_b128 v[202:205], v157 offset:21504
	ds_read_b128 v[206:209], v157 offset:22528
	ds_read_b128 v[210:213], v157 offset:23552
	global_load_lds_dwordx4 v[214:215], off
	s_add_i32 m0, s48, 0x2000
	s_add_u32 s48, s22, 0x100000
	v_lshl_add_u64 v[216:217], s[22:23], 0, v[134:135]
	s_addc_u32 s49, s23, 0
	s_add_i32 s50, s41, s31
	global_load_lds_dwordx4 v[216:217], off
	v_lshl_add_u64 v[218:219], s[48:49], 0, v[130:131]
	s_mov_b32 m0, s50
	v_lshl_add_u64 v[220:221], s[24:25], 0, v[132:133]
	global_load_lds_dwordx4 v[218:219], off
	v_lshl_add_u64 v[218:219], s[48:49], 0, v[134:135]
	s_add_i32 m0, s50, 0x2000
	s_nop 0
	global_load_lds_dwordx4 v[218:219], off
	v_lshl_add_u64 v[218:219], s[24:25], 0, v[128:129]
	s_mov_b32 m0, s19
	s_nop 0
	global_load_lds_dwordx4 v[218:219], off
	s_mov_b32 m0, s33
	s_nop 0
	global_load_lds_dwordx4 v[220:221], off
	s_waitcnt vmcnt(8)
	s_waitcnt lgkmcnt(0)
	s_barrier
	s_setprio 1
	s_waitcnt lgkmcnt(0)
	v_mfma_f32_16x16x32_bf16 v[60:63], v[144:147], v[182:185], v[60:63]
	v_mfma_f32_16x16x32_bf16 v[56:59], v[158:161], v[182:185], v[56:59]
	v_mfma_f32_16x16x32_bf16 v[44:47], v[144:147], v[190:193], v[44:47]
	v_mfma_f32_16x16x32_bf16 v[40:43], v[158:161], v[190:193], v[40:43]
	v_mfma_f32_16x16x32_bf16 v[28:31], v[144:147], v[198:201], v[28:31]
	v_mfma_f32_16x16x32_bf16 v[24:27], v[158:161], v[198:201], v[24:27]
	v_mfma_f32_16x16x32_bf16 v[12:15], v[144:147], v[206:209], v[12:15]
	v_mfma_f32_16x16x32_bf16 v[8:11], v[158:161], v[206:209], v[8:11]
	v_mfma_f32_16x16x32_bf16 v[60:63], v[148:151], v[186:189], v[60:63]
	v_mfma_f32_16x16x32_bf16 v[56:59], v[162:165], v[186:189], v[56:59]
	v_mfma_f32_16x16x32_bf16 v[44:47], v[148:151], v[194:197], v[44:47]
	v_mfma_f32_16x16x32_bf16 v[40:43], v[162:165], v[194:197], v[40:43]
	v_mfma_f32_16x16x32_bf16 v[28:31], v[148:151], v[202:205], v[28:31]
	v_mfma_f32_16x16x32_bf16 v[24:27], v[162:165], v[202:205], v[24:27]
	v_mfma_f32_16x16x32_bf16 v[12:15], v[148:151], v[210:213], v[12:15]
	v_mfma_f32_16x16x32_bf16 v[8:11], v[162:165], v[210:213], v[8:11]
	s_setprio 0
	s_setprio 1
	v_mfma_f32_16x16x32_bf16 v[52:55], v[166:169], v[182:185], v[52:55]
	v_mfma_f32_16x16x32_bf16 v[48:51], v[174:177], v[182:185], v[48:51]
	v_mfma_f32_16x16x32_bf16 v[36:39], v[166:169], v[190:193], v[36:39]
	v_mfma_f32_16x16x32_bf16 v[32:35], v[174:177], v[190:193], v[32:35]
	v_mfma_f32_16x16x32_bf16 v[20:23], v[166:169], v[198:201], v[20:23]
	v_mfma_f32_16x16x32_bf16 v[16:19], v[174:177], v[198:201], v[16:19]
	v_mfma_f32_16x16x32_bf16 v[4:7], v[166:169], v[206:209], v[4:7]
	v_mfma_f32_16x16x32_bf16 v[0:3], v[174:177], v[206:209], v[0:3]
	v_mfma_f32_16x16x32_bf16 v[52:55], v[170:173], v[186:189], v[52:55]
	v_mfma_f32_16x16x32_bf16 v[48:51], v[178:181], v[186:189], v[48:51]
	v_mfma_f32_16x16x32_bf16 v[36:39], v[170:173], v[194:197], v[36:39]
	v_mfma_f32_16x16x32_bf16 v[32:35], v[178:181], v[194:197], v[32:35]
	v_mfma_f32_16x16x32_bf16 v[20:23], v[170:173], v[202:205], v[20:23]
	v_mfma_f32_16x16x32_bf16 v[16:19], v[178:181], v[202:205], v[16:19]
	v_mfma_f32_16x16x32_bf16 v[4:7], v[170:173], v[210:213], v[4:7]
	v_mfma_f32_16x16x32_bf16 v[0:3], v[178:181], v[210:213], v[0:3]
	s_setprio 0
	s_barrier
	s_add_i32 s48, 0, 0x18000
	s_add_i32 s49, 0, 0x1c000
	v_add_u32_e32 v162, s48, v153
	v_add_u32_e32 v178, s49, v153
	ds_read_b128 v[144:147], v162
	ds_read_b128 v[148:151], v162 offset:1024
	ds_read_b128 v[158:161], v162 offset:2048
	ds_read_b128 v[162:165], v162 offset:3072
	ds_read_b128 v[166:169], v178
	ds_read_b128 v[170:173], v178 offset:1024
	ds_read_b128 v[174:177], v178 offset:2048
	ds_read_b128 v[178:181], v178 offset:3072
	s_add_u32 s24, s24, 0x100000
	s_addc_u32 s25, s25, 0
	s_mov_b32 m0, s34
	v_lshl_add_u64 v[222:223], s[24:25], 0, v[128:129]
	ds_read_b128 v[182:185], v157 offset:32768
	ds_read_b128 v[186:189], v157 offset:33792
	ds_read_b128 v[190:193], v157 offset:34816
	ds_read_b128 v[194:197], v157 offset:35840
	ds_read_b128 v[198:201], v157 offset:36864
	ds_read_b128 v[202:205], v157 offset:37888
	ds_read_b128 v[206:209], v157 offset:38912
	ds_read_b128 v[210:213], v157 offset:39936
	global_load_lds_dwordx4 v[222:223], off
	v_lshl_add_u64 v[222:223], s[24:25], 0, v[132:133]
	s_mov_b32 m0, s35
	s_nop 0
	global_load_lds_dwordx4 v[222:223], off
	s_waitcnt vmcnt(8)
	s_waitcnt lgkmcnt(0)
	s_barrier
	s_setprio 1
	s_waitcnt lgkmcnt(0)
	v_mfma_f32_16x16x32_bf16 v[124:127], v[144:147], v[182:185], v[124:127]
	v_mfma_f32_16x16x32_bf16 v[120:123], v[158:161], v[182:185], v[120:123]
	v_mfma_f32_16x16x32_bf16 v[108:111], v[144:147], v[190:193], v[108:111]
	v_mfma_f32_16x16x32_bf16 v[104:107], v[158:161], v[190:193], v[104:107]
	v_mfma_f32_16x16x32_bf16 v[92:95], v[144:147], v[198:201], v[92:95]
	v_mfma_f32_16x16x32_bf16 v[88:91], v[158:161], v[198:201], v[88:91]
	v_mfma_f32_16x16x32_bf16 v[76:79], v[144:147], v[206:209], v[76:79]
	v_mfma_f32_16x16x32_bf16 v[72:75], v[158:161], v[206:209], v[72:75]
	v_mfma_f32_16x16x32_bf16 v[124:127], v[148:151], v[186:189], v[124:127]
	v_mfma_f32_16x16x32_bf16 v[120:123], v[162:165], v[186:189], v[120:123]
	v_mfma_f32_16x16x32_bf16 v[108:111], v[148:151], v[194:197], v[108:111]
	v_mfma_f32_16x16x32_bf16 v[104:107], v[162:165], v[194:197], v[104:107]
	v_mfma_f32_16x16x32_bf16 v[92:95], v[148:151], v[202:205], v[92:95]
	v_mfma_f32_16x16x32_bf16 v[88:91], v[162:165], v[202:205], v[88:91]
	v_mfma_f32_16x16x32_bf16 v[76:79], v[148:151], v[210:213], v[76:79]
	v_mfma_f32_16x16x32_bf16 v[72:75], v[162:165], v[210:213], v[72:75]
	s_setprio 0
	s_setprio 1
	v_mfma_f32_16x16x32_bf16 v[116:119], v[166:169], v[182:185], v[116:119]
	v_mfma_f32_16x16x32_bf16 v[112:115], v[174:177], v[182:185], v[112:115]
	v_mfma_f32_16x16x32_bf16 v[100:103], v[166:169], v[190:193], v[100:103]
	v_mfma_f32_16x16x32_bf16 v[96:99], v[174:177], v[190:193], v[96:99]
	v_mfma_f32_16x16x32_bf16 v[84:87], v[166:169], v[198:201], v[84:87]
	v_mfma_f32_16x16x32_bf16 v[80:83], v[174:177], v[198:201], v[80:83]
	v_mfma_f32_16x16x32_bf16 v[68:71], v[166:169], v[206:209], v[68:71]
	v_mfma_f32_16x16x32_bf16 v[64:67], v[174:177], v[206:209], v[64:67]
	v_mfma_f32_16x16x32_bf16 v[116:119], v[170:173], v[186:189], v[116:119]
	v_mfma_f32_16x16x32_bf16 v[112:115], v[178:181], v[186:189], v[112:115]
	v_mfma_f32_16x16x32_bf16 v[100:103], v[170:173], v[194:197], v[100:103]
	v_mfma_f32_16x16x32_bf16 v[96:99], v[178:181], v[194:197], v[96:99]
	v_mfma_f32_16x16x32_bf16 v[84:87], v[170:173], v[202:205], v[84:87]
	v_mfma_f32_16x16x32_bf16 v[80:83], v[178:181], v[202:205], v[80:83]
	v_mfma_f32_16x16x32_bf16 v[68:71], v[170:173], v[210:213], v[68:71]
	v_mfma_f32_16x16x32_bf16 v[64:67], v[178:181], v[210:213], v[64:67]
	s_setprio 0
	s_barrier
	s_add_i32 s24, s48, s31
	v_lshl_add_u64 v[214:215], v[214:215], 0, s[6:7]
	s_mov_b32 m0, s24
	ds_read_b128 v[182:185], v157 offset:49152
	ds_read_b128 v[186:189], v157 offset:50176
	ds_read_b128 v[190:193], v157 offset:51200
	ds_read_b128 v[194:197], v157 offset:52224
	ds_read_b128 v[198:201], v157 offset:53248
	ds_read_b128 v[202:205], v157 offset:54272
	ds_read_b128 v[206:209], v157 offset:55296
	ds_read_b128 v[210:213], v157 offset:56320
	global_load_lds_dwordx4 v[214:215], off
	s_add_i32 m0, s24, 0x2000
	s_add_u32 s22, s22, 0x100080
	v_lshl_add_u64 v[214:215], v[216:217], 0, s[6:7]
	s_addc_u32 s23, s23, 0
	s_add_i32 s24, s49, s31
	global_load_lds_dwordx4 v[214:215], off
	v_lshl_add_u64 v[214:215], s[22:23], 0, v[130:131]
	s_mov_b32 m0, s24
	s_nop 0
	global_load_lds_dwordx4 v[214:215], off
	v_lshl_add_u64 v[214:215], s[22:23], 0, v[134:135]
	s_add_i32 m0, s24, 0x2000
	s_nop 0
	global_load_lds_dwordx4 v[214:215], off
	v_lshl_add_u64 v[214:215], v[218:219], 0, s[6:7]
	s_mov_b32 m0, s37
	s_nop 0
	global_load_lds_dwordx4 v[214:215], off
	v_lshl_add_u64 v[214:215], v[220:221], 0, s[6:7]
	s_mov_b32 m0, s38
	s_nop 0
	global_load_lds_dwordx4 v[214:215], off
	s_waitcnt vmcnt(8)
	s_waitcnt lgkmcnt(0)
	s_barrier
	s_setprio 1
	s_waitcnt lgkmcnt(0)
	v_mfma_f32_16x16x32_bf16 v[60:63], v[144:147], v[182:185], v[60:63]
	v_mfma_f32_16x16x32_bf16 v[56:59], v[158:161], v[182:185], v[56:59]
	v_mfma_f32_16x16x32_bf16 v[44:47], v[144:147], v[190:193], v[44:47]
	v_mfma_f32_16x16x32_bf16 v[40:43], v[158:161], v[190:193], v[40:43]
	v_mfma_f32_16x16x32_bf16 v[28:31], v[144:147], v[198:201], v[28:31]
	v_mfma_f32_16x16x32_bf16 v[24:27], v[158:161], v[198:201], v[24:27]
	v_mfma_f32_16x16x32_bf16 v[12:15], v[144:147], v[206:209], v[12:15]
	v_mfma_f32_16x16x32_bf16 v[8:11], v[158:161], v[206:209], v[8:11]
	v_mfma_f32_16x16x32_bf16 v[60:63], v[148:151], v[186:189], v[60:63]
	v_mfma_f32_16x16x32_bf16 v[56:59], v[162:165], v[186:189], v[56:59]
	v_mfma_f32_16x16x32_bf16 v[44:47], v[148:151], v[194:197], v[44:47]
	v_mfma_f32_16x16x32_bf16 v[40:43], v[162:165], v[194:197], v[40:43]
	v_mfma_f32_16x16x32_bf16 v[28:31], v[148:151], v[202:205], v[28:31]
	v_mfma_f32_16x16x32_bf16 v[24:27], v[162:165], v[202:205], v[24:27]
	v_mfma_f32_16x16x32_bf16 v[12:15], v[148:151], v[210:213], v[12:15]
	v_mfma_f32_16x16x32_bf16 v[8:11], v[162:165], v[210:213], v[8:11]
	s_setprio 0
	s_setprio 1
	s_add_i32 s47, s47, 2
	s_add_u32 s20, s20, 0x100
	s_addc_u32 s21, s21, 0
	s_add_u32 s45, s45, 0x100
	s_addc_u32 s46, s46, 0
	s_cmp_gt_u32 s47, 61
	v_mfma_f32_16x16x32_bf16 v[52:55], v[166:169], v[182:185], v[52:55]
	v_mfma_f32_16x16x32_bf16 v[48:51], v[174:177], v[182:185], v[48:51]
	v_mfma_f32_16x16x32_bf16 v[36:39], v[166:169], v[190:193], v[36:39]
	v_mfma_f32_16x16x32_bf16 v[32:35], v[174:177], v[190:193], v[32:35]
	v_mfma_f32_16x16x32_bf16 v[20:23], v[166:169], v[198:201], v[20:23]
	v_mfma_f32_16x16x32_bf16 v[16:19], v[174:177], v[198:201], v[16:19]
	v_mfma_f32_16x16x32_bf16 v[4:7], v[166:169], v[206:209], v[4:7]
	v_mfma_f32_16x16x32_bf16 v[0:3], v[174:177], v[206:209], v[0:3]
	v_mfma_f32_16x16x32_bf16 v[52:55], v[170:173], v[186:189], v[52:55]
	v_mfma_f32_16x16x32_bf16 v[48:51], v[178:181], v[186:189], v[48:51]
	v_mfma_f32_16x16x32_bf16 v[36:39], v[170:173], v[194:197], v[36:39]
	v_mfma_f32_16x16x32_bf16 v[32:35], v[178:181], v[194:197], v[32:35]
	v_mfma_f32_16x16x32_bf16 v[20:23], v[170:173], v[202:205], v[20:23]
	v_mfma_f32_16x16x32_bf16 v[16:19], v[178:181], v[202:205], v[16:19]
	v_mfma_f32_16x16x32_bf16 v[4:7], v[170:173], v[210:213], v[4:7]
	v_mfma_f32_16x16x32_bf16 v[0:3], v[178:181], v[210:213], v[0:3]
	s_setprio 0
	s_barrier
	s_cbranch_scc0 .LBB0_1051
	s_and_b64 vcc, exec, s[8:9]
	s_cbranch_vccz .LBB0_1054
	s_barrier
